# BM selected-attention: K fragments of block i+2 issued right after the last QK of block i (K prefetch distance ~2 blocks, list entries fetched 3 ahead)
# baseline (speedup 1.0000x reference)
.LBB0_1549:
.LBB0_1550:
	v_readfirstlane_b32 s46, v70
	v_readfirstlane_b32 s47, v71
	v_readfirstlane_b32 s62, v72
	v_readfirstlane_b32 s63, v73
	v_and_b32_e32 v248, 15, v181
	v_lshrrev_b32_e32 v249, 4, v181
	v_lshrrev_b32_e32 v248, 2, v248
	v_lshlrev_b32_e32 v249, 2, v249
	v_readlane_b32 s23, v243, 32
	v_mov_b32_e32 v244, 1
	v_lshlrev_b32_e32 v244, v248, v244
	s_mov_b32 s16, 0x3e38aa3b
	s_mov_b32 s17, 0x3e38aa3b
	v_lshlrev_b32_e32 v79, 4, v181
	s_add_i32 s23, s23, s97
	v_add_u32_e32 v247, s23, v248
	v_mad_u64_u32 v[250:251], s[50:51], v247, v212, v[68:69]
	global_load_dwordx4 v[100:103], v[250:251], off
	global_load_dwordx4 v[104:107], v[250:251], off offset:64
	v_add_u32_e32 v249, 4, v247
	v_mad_u64_u32 v[250:251], s[50:51], v249, v212, v[68:69]
	global_load_dwordx4 v[108:111], v[250:251], off
	global_load_dwordx4 v[112:115], v[250:251], off offset:64
	v_add_u32_e32 v249, 8, v247
	v_mad_u64_u32 v[250:251], s[50:51], v249, v212, v[68:69]
	global_load_dwordx4 v[116:119], v[250:251], off
	global_load_dwordx4 v[120:123], v[250:251], off offset:64
	v_add_u32_e32 v249, 12, v247
	v_mad_u64_u32 v[250:251], s[50:51], v249, v212, v[68:69]
	global_load_dwordx4 v[124:127], v[250:251], off
	global_load_dwordx4 v[128:131], v[250:251], off offset:64
	v_and_b32_e32 v248, 15, v181
	v_lshrrev_b32_e32 v249, 4, v181
	v_lshlrev_b32_e32 v198, 6, v248
	v_lshl_add_u32 v198, v249, 2, v198
	v_add_u32_e32 v198, s96, v198
	v_lshl_add_u32 v199, v248, 2, s96
	ds_read_b32 v12, v198 offset:16384
	ds_read_b32 v13, v198 offset:16400
	ds_read_b32 v14, v198 offset:16416
	ds_read_b32 v15, v198 offset:16432
	ds_read_b32 v16, v199 offset:17408
	v_lshl_add_u32 v199, v181, 2, s96
	v_mov_b32_e32 v17, 1
	v_lshlrev_b32_e32 v17, v248, v17
	s_waitcnt lgkmcnt(0)
	v_mul_f32_e32 v81, 0x3fb8aa3b, v81
	ds_write_b32 v199, v11 offset:16384
	ds_write_b32 v199, v11 offset:16640
	ds_write_b32 v199, v11 offset:16896
	ds_write_b32 v199, v11 offset:17152
	v_cmp_lt_i32_e32 vcc, v249, v16
	v_and_b32_e32 v12, 0xff, v12
	v_lshl_add_u32 v12, v12, 2, s96
	v_cndmask_b32_e32 v18, 0, v17, vcc
	ds_or_b32 v12, v18 offset:16384
	v_add_u32_e32 v18, 4, v249
	v_cmp_lt_i32_e32 vcc, v18, v16
	v_and_b32_e32 v13, 0xff, v13
	v_lshl_add_u32 v13, v13, 2, s96
	v_cndmask_b32_e32 v18, 0, v17, vcc
	ds_or_b32 v13, v18 offset:16384
	v_add_u32_e32 v18, 8, v249
	v_cmp_lt_i32_e32 vcc, v18, v16
	v_and_b32_e32 v14, 0xff, v14
	v_lshl_add_u32 v14, v14, 2, s96
	v_cndmask_b32_e32 v18, 0, v17, vcc
	ds_or_b32 v14, v18 offset:16384
	v_add_u32_e32 v18, 12, v249
	v_cmp_lt_i32_e32 vcc, v18, v16
	v_and_b32_e32 v15, 0xff, v15
	v_lshl_add_u32 v15, v15, 2, s96
	v_cndmask_b32_e32 v18, 0, v17, vcc
	ds_or_b32 v15, v18 offset:16384
	s_waitcnt lgkmcnt(0)
	ds_read_b32 v12, v199 offset:16384
	ds_read_b32 v13, v199 offset:16640
	ds_read_b32 v14, v199 offset:16896
	ds_read_b32 v15, v199 offset:17152
	s_mov_b32 s25, 0
	s_waitcnt lgkmcnt(0)
	v_cmp_ne_u32_e64 s[4:5], 0, v12
	v_lshlrev_b32_e32 v16, 16, v12
	v_add_u32_e32 v17, 0, v181
	v_or_b32_e32 v16, v16, v17
	v_mbcnt_lo_u32_b32 v17, s4, 0
	v_mbcnt_hi_u32_b32 v17, s5, v17
	v_add_u32_e32 v17, s25, v17
	v_lshl_add_u32 v17, v17, 2, s96
	v_add_u32_e32 v17, 0x4000, v17
	v_add_u32_e32 v18, 0x4400, v199
	s_bcnt1_i32_b64 s13, s[4:5]
	v_cndmask_b32_e64 v17, v18, v17, s[4:5]
	s_add_i32 s25, s25, s13
	ds_write_b32 v17, v16
	v_cmp_ne_u32_e64 s[4:5], 0, v13
	v_lshlrev_b32_e32 v16, 16, v13
	v_add_u32_e32 v17, 64, v181
	v_or_b32_e32 v16, v16, v17
	v_mbcnt_lo_u32_b32 v17, s4, 0
	v_mbcnt_hi_u32_b32 v17, s5, v17
	v_add_u32_e32 v17, s25, v17
	v_lshl_add_u32 v17, v17, 2, s96
	v_add_u32_e32 v17, 0x4000, v17
	v_add_u32_e32 v18, 0x4400, v199
	s_bcnt1_i32_b64 s13, s[4:5]
	v_cndmask_b32_e64 v17, v18, v17, s[4:5]
	s_add_i32 s25, s25, s13
	ds_write_b32 v17, v16
	v_cmp_ne_u32_e64 s[4:5], 0, v14
	v_lshlrev_b32_e32 v16, 16, v14
	v_add_u32_e32 v17, 128, v181
	v_or_b32_e32 v16, v16, v17
	v_mbcnt_lo_u32_b32 v17, s4, 0
	v_mbcnt_hi_u32_b32 v17, s5, v17
	v_add_u32_e32 v17, s25, v17
	v_lshl_add_u32 v17, v17, 2, s96
	v_add_u32_e32 v17, 0x4000, v17
	v_add_u32_e32 v18, 0x4400, v199
	s_bcnt1_i32_b64 s13, s[4:5]
	v_cndmask_b32_e64 v17, v18, v17, s[4:5]
	s_add_i32 s25, s25, s13
	ds_write_b32 v17, v16
	v_cmp_ne_u32_e64 s[4:5], 0, v15
	v_lshlrev_b32_e32 v16, 16, v15
	v_add_u32_e32 v17, 192, v181
	v_or_b32_e32 v16, v16, v17
	v_mbcnt_lo_u32_b32 v17, s4, 0
	v_mbcnt_hi_u32_b32 v17, s5, v17
	v_add_u32_e32 v17, s25, v17
	v_lshl_add_u32 v17, v17, 2, s96
	v_add_u32_e32 v17, 0x4000, v17
	v_add_u32_e32 v18, 0x4400, v199
	s_bcnt1_i32_b64 s13, s[4:5]
	v_cndmask_b32_e64 v17, v18, v17, s[4:5]
	s_add_i32 s25, s25, s13
	ds_write_b32 v17, v16
	s_waitcnt vmcnt(0)
	v_lshlrev_b32_e32 v245, 16, v100
	v_and_b32_e32 v246, 0xffff0000, v100
	v_mul_f32_e32 v245, 0x41000000, v245
	v_mul_f32_e32 v246, 0x41000000, v246
	v_lshlrev_b32_e32 v248, 16, v101
	v_and_b32_e32 v249, 0xffff0000, v101
	v_cvt_pk_fp8_f32 v164, v245, v246
	v_mul_f32_e32 v248, 0x41000000, v248
	v_mul_f32_e32 v249, 0x41000000, v249
	s_nop 0
	v_cvt_pk_fp8_f32 v164, v248, v249 op_sel:[0,0,1]
	v_lshlrev_b32_e32 v245, 16, v102
	v_and_b32_e32 v246, 0xffff0000, v102
	v_mul_f32_e32 v245, 0x41000000, v245
	v_mul_f32_e32 v246, 0x41000000, v246
	v_lshlrev_b32_e32 v248, 16, v103
	v_and_b32_e32 v249, 0xffff0000, v103
	v_cvt_pk_fp8_f32 v165, v245, v246
	v_mul_f32_e32 v248, 0x41000000, v248
	v_mul_f32_e32 v249, 0x41000000, v249
	s_nop 0
	v_cvt_pk_fp8_f32 v165, v248, v249 op_sel:[0,0,1]
	v_lshlrev_b32_e32 v245, 16, v104
	v_and_b32_e32 v246, 0xffff0000, v104
	v_mul_f32_e32 v245, 0x41000000, v245
	v_mul_f32_e32 v246, 0x41000000, v246
	v_lshlrev_b32_e32 v248, 16, v105
	v_and_b32_e32 v249, 0xffff0000, v105
	v_cvt_pk_fp8_f32 v166, v245, v246
	v_mul_f32_e32 v248, 0x41000000, v248
	v_mul_f32_e32 v249, 0x41000000, v249
	s_nop 0
	v_cvt_pk_fp8_f32 v166, v248, v249 op_sel:[0,0,1]
	v_lshlrev_b32_e32 v245, 16, v106
	v_and_b32_e32 v246, 0xffff0000, v106
	v_mul_f32_e32 v245, 0x41000000, v245
	v_mul_f32_e32 v246, 0x41000000, v246
	v_lshlrev_b32_e32 v248, 16, v107
	v_and_b32_e32 v249, 0xffff0000, v107
	v_cvt_pk_fp8_f32 v167, v245, v246
	v_mul_f32_e32 v248, 0x41000000, v248
	v_mul_f32_e32 v249, 0x41000000, v249
	s_nop 0
	v_cvt_pk_fp8_f32 v167, v248, v249 op_sel:[0,0,1]
	v_lshlrev_b32_e32 v245, 16, v108
	v_and_b32_e32 v246, 0xffff0000, v108
	v_mul_f32_e32 v245, 0x41000000, v245
	v_mul_f32_e32 v246, 0x41000000, v246
	v_lshlrev_b32_e32 v248, 16, v109
	v_and_b32_e32 v249, 0xffff0000, v109
	v_cvt_pk_fp8_f32 v168, v245, v246
	v_mul_f32_e32 v248, 0x41000000, v248
	v_mul_f32_e32 v249, 0x41000000, v249
	s_nop 0
	v_cvt_pk_fp8_f32 v168, v248, v249 op_sel:[0,0,1]
	v_lshlrev_b32_e32 v245, 16, v110
	v_and_b32_e32 v246, 0xffff0000, v110
	v_mul_f32_e32 v245, 0x41000000, v245
	v_mul_f32_e32 v246, 0x41000000, v246
	v_lshlrev_b32_e32 v248, 16, v111
	v_and_b32_e32 v249, 0xffff0000, v111
	v_cvt_pk_fp8_f32 v169, v245, v246
	v_mul_f32_e32 v248, 0x41000000, v248
	v_mul_f32_e32 v249, 0x41000000, v249
	s_nop 0
	v_cvt_pk_fp8_f32 v169, v248, v249 op_sel:[0,0,1]
	v_lshlrev_b32_e32 v245, 16, v112
	v_and_b32_e32 v246, 0xffff0000, v112
	v_mul_f32_e32 v245, 0x41000000, v245
	v_mul_f32_e32 v246, 0x41000000, v246
	v_lshlrev_b32_e32 v248, 16, v113
	v_and_b32_e32 v249, 0xffff0000, v113
	v_cvt_pk_fp8_f32 v170, v245, v246
	v_mul_f32_e32 v248, 0x41000000, v248
	v_mul_f32_e32 v249, 0x41000000, v249
	s_nop 0
	v_cvt_pk_fp8_f32 v170, v248, v249 op_sel:[0,0,1]
	v_lshlrev_b32_e32 v245, 16, v114
	v_and_b32_e32 v246, 0xffff0000, v114
	v_mul_f32_e32 v245, 0x41000000, v245
	v_mul_f32_e32 v246, 0x41000000, v246
	v_lshlrev_b32_e32 v248, 16, v115
	v_and_b32_e32 v249, 0xffff0000, v115
	v_cvt_pk_fp8_f32 v171, v245, v246
	v_mul_f32_e32 v248, 0x41000000, v248
	v_mul_f32_e32 v249, 0x41000000, v249
	s_nop 0
	v_cvt_pk_fp8_f32 v171, v248, v249 op_sel:[0,0,1]
	v_lshlrev_b32_e32 v245, 16, v116
	v_and_b32_e32 v246, 0xffff0000, v116
	v_mul_f32_e32 v245, 0x41000000, v245
	v_mul_f32_e32 v246, 0x41000000, v246
	v_lshlrev_b32_e32 v248, 16, v117
	v_and_b32_e32 v249, 0xffff0000, v117
	v_cvt_pk_fp8_f32 v182, v245, v246
	v_mul_f32_e32 v248, 0x41000000, v248
	v_mul_f32_e32 v249, 0x41000000, v249
	s_nop 0
	v_cvt_pk_fp8_f32 v182, v248, v249 op_sel:[0,0,1]
	v_lshlrev_b32_e32 v245, 16, v118
	v_and_b32_e32 v246, 0xffff0000, v118
	v_mul_f32_e32 v245, 0x41000000, v245
	v_mul_f32_e32 v246, 0x41000000, v246
	v_lshlrev_b32_e32 v248, 16, v119
	v_and_b32_e32 v249, 0xffff0000, v119
	v_cvt_pk_fp8_f32 v183, v245, v246
	v_mul_f32_e32 v248, 0x41000000, v248
	v_mul_f32_e32 v249, 0x41000000, v249
	s_nop 0
	v_cvt_pk_fp8_f32 v183, v248, v249 op_sel:[0,0,1]
	v_lshlrev_b32_e32 v245, 16, v120
	v_and_b32_e32 v246, 0xffff0000, v120
	v_mul_f32_e32 v245, 0x41000000, v245
	v_mul_f32_e32 v246, 0x41000000, v246
	v_lshlrev_b32_e32 v248, 16, v121
	v_and_b32_e32 v249, 0xffff0000, v121
	v_cvt_pk_fp8_f32 v184, v245, v246
	v_mul_f32_e32 v248, 0x41000000, v248
	v_mul_f32_e32 v249, 0x41000000, v249
	s_nop 0
	v_cvt_pk_fp8_f32 v184, v248, v249 op_sel:[0,0,1]
	v_lshlrev_b32_e32 v245, 16, v122
	v_and_b32_e32 v246, 0xffff0000, v122
	v_mul_f32_e32 v245, 0x41000000, v245
	v_mul_f32_e32 v246, 0x41000000, v246
	v_lshlrev_b32_e32 v248, 16, v123
	v_and_b32_e32 v249, 0xffff0000, v123
	v_cvt_pk_fp8_f32 v185, v245, v246
	v_mul_f32_e32 v248, 0x41000000, v248
	v_mul_f32_e32 v249, 0x41000000, v249
	s_nop 0
	v_cvt_pk_fp8_f32 v185, v248, v249 op_sel:[0,0,1]
	v_lshlrev_b32_e32 v245, 16, v124
	v_and_b32_e32 v246, 0xffff0000, v124
	v_mul_f32_e32 v245, 0x41000000, v245
	v_mul_f32_e32 v246, 0x41000000, v246
	v_lshlrev_b32_e32 v248, 16, v125
	v_and_b32_e32 v249, 0xffff0000, v125
	v_cvt_pk_fp8_f32 v186, v245, v246
	v_mul_f32_e32 v248, 0x41000000, v248
	v_mul_f32_e32 v249, 0x41000000, v249
	s_nop 0
	v_cvt_pk_fp8_f32 v186, v248, v249 op_sel:[0,0,1]
	v_lshlrev_b32_e32 v245, 16, v126
	v_and_b32_e32 v246, 0xffff0000, v126
	v_mul_f32_e32 v245, 0x41000000, v245
	v_mul_f32_e32 v246, 0x41000000, v246
	v_lshlrev_b32_e32 v248, 16, v127
	v_and_b32_e32 v249, 0xffff0000, v127
	v_cvt_pk_fp8_f32 v187, v245, v246
	v_mul_f32_e32 v248, 0x41000000, v248
	v_mul_f32_e32 v249, 0x41000000, v249
	s_nop 0
	v_cvt_pk_fp8_f32 v187, v248, v249 op_sel:[0,0,1]
	v_lshlrev_b32_e32 v245, 16, v128
	v_and_b32_e32 v246, 0xffff0000, v128
	v_mul_f32_e32 v245, 0x41000000, v245
	v_mul_f32_e32 v246, 0x41000000, v246
	v_lshlrev_b32_e32 v248, 16, v129
	v_and_b32_e32 v249, 0xffff0000, v129
	v_cvt_pk_fp8_f32 v188, v245, v246
	v_mul_f32_e32 v248, 0x41000000, v248
	v_mul_f32_e32 v249, 0x41000000, v249
	s_nop 0
	v_cvt_pk_fp8_f32 v188, v248, v249 op_sel:[0,0,1]
	v_lshlrev_b32_e32 v245, 16, v130
	v_and_b32_e32 v246, 0xffff0000, v130
	v_mul_f32_e32 v245, 0x41000000, v245
	v_mul_f32_e32 v246, 0x41000000, v246
	v_lshlrev_b32_e32 v248, 16, v131
	v_and_b32_e32 v249, 0xffff0000, v131
	v_cvt_pk_fp8_f32 v189, v245, v246
	v_mul_f32_e32 v248, 0x41000000, v248
	v_mul_f32_e32 v249, 0x41000000, v249
	s_nop 0
	v_cvt_pk_fp8_f32 v189, v248, v249 op_sel:[0,0,1]
	v_mov_b64_e32 v[100:101], 0
	v_mov_b64_e32 v[102:103], 0
	v_mov_b64_e32 v[104:105], 0
	v_mov_b64_e32 v[106:107], 0
	v_mov_b64_e32 v[108:109], 0
	v_mov_b64_e32 v[110:111], 0
	v_mov_b64_e32 v[112:113], 0
	v_mov_b64_e32 v[114:115], 0
	v_mov_b32_e32 v190, 0
	v_mov_b32_e32 v194, 0
	v_mov_b64_e32 v[116:117], 0
	v_mov_b64_e32 v[118:119], 0
	v_mov_b64_e32 v[120:121], 0
	v_mov_b64_e32 v[122:123], 0
	v_mov_b64_e32 v[124:125], 0
	v_mov_b64_e32 v[126:127], 0
	v_mov_b64_e32 v[128:129], 0
	v_mov_b64_e32 v[130:131], 0
	v_mov_b32_e32 v191, 0
	v_mov_b32_e32 v195, 0
	v_mov_b64_e32 v[132:133], 0
	v_mov_b64_e32 v[134:135], 0
	v_mov_b64_e32 v[136:137], 0
	v_mov_b64_e32 v[138:139], 0
	v_mov_b64_e32 v[140:141], 0
	v_mov_b64_e32 v[142:143], 0
	v_mov_b64_e32 v[144:145], 0
	v_mov_b64_e32 v[146:147], 0
	v_mov_b32_e32 v192, 0
	v_mov_b32_e32 v196, 0
	v_mov_b64_e32 v[148:149], 0
	v_mov_b64_e32 v[150:151], 0
	v_mov_b64_e32 v[152:153], 0
	v_mov_b64_e32 v[154:155], 0
	v_mov_b64_e32 v[156:157], 0
	v_mov_b64_e32 v[158:159], 0
	v_mov_b64_e32 v[160:161], 0
	v_mov_b64_e32 v[162:163], 0
	v_mov_b32_e32 v193, 0
	v_mov_b32_e32 v197, 0
	v_mov_b32_e32 v77, 0xff800000
	v_mov_b32_e32 v78, 0xff800000
	s_waitcnt lgkmcnt(0)
	s_mov_b32 s35, 0
	s_lshl_b32 s13, s35, 2
	s_add_i32 s13, s13, s96
	v_mov_b32_e32 v76, s13
	ds_read_b32 v76, v76 offset:16384
	s_add_i32 s14, s25, -1
	s_min_i32 s14, s14, 1
	s_waitcnt lgkmcnt(0)
	v_readfirstlane_b32 s13, v76
	s_and_b32 s54, s13, 0xffff
	s_lshr_b32 s48, s13, 16
	s_lshl_b32 s13, s14, 2
	s_add_i32 s13, s13, s96
	v_mov_b32_e32 v76, s13
	ds_read_b32 v76, v76 offset:16384
	s_lshl_b32 s12, s54, 12
	s_add_u32 s30, s46, s12
	s_addc_u32 s31, s47, 0
	global_load_dwordx4 v[2:5], v79, s[30:31]
	global_load_dwordx4 v[6:9], v79, s[30:31] offset:1024
	global_load_dwordx4 v[12:15], v79, s[30:31] offset:2048
	global_load_dwordx4 v[16:19], v79, s[30:31] offset:3072
	s_lshl_b32 s12, s54, 12
	s_add_u32 s30, s62, s12
	s_addc_u32 s31, s63, 0
	global_load_dwordx4 v[36:39], v79, s[30:31]
	global_load_dwordx4 v[40:43], v79, s[30:31] offset:1024
	global_load_dwordx4 v[44:47], v79, s[30:31] offset:2048
	global_load_dwordx4 v[48:51], v79, s[30:31] offset:3072
	s_waitcnt lgkmcnt(0)
	v_readfirstlane_b32 s13, v76
	s_and_b32 s15, s13, 0xffff
	s_lshr_b32 s27, s13, 16
	s_add_i32 s83, s25, -1
	s_min_i32 s83, s83, 2
	s_lshl_b32 s83, s83, 2
	s_add_i32 s83, s83, s96
	v_mov_b32_e32 v76, s83
	ds_read_b32 v76, v76 offset:16384
	s_lshl_b32 s83, s15, 12
	s_add_u32 s30, s46, s83
	s_addc_u32 s31, s47, 0
	global_load_dwordx4 v[20:23], v79, s[30:31]
	global_load_dwordx4 v[24:27], v79, s[30:31] offset:1024
	global_load_dwordx4 v[28:31], v79, s[30:31] offset:2048
	global_load_dwordx4 v[32:35], v79, s[30:31] offset:3072
	s_waitcnt lgkmcnt(0)
	v_readfirstlane_b32 s13, v76
	s_and_b32 s32, s13, 0xffff
	s_lshr_b32 s55, s13, 16
.Lbm2_blkA:
	s_lshl_b32 s12, s15, 12
	s_add_u32 s30, s62, s12
	s_addc_u32 s31, s63, 0
	global_load_dwordx4 v[52:55], v79, s[30:31]
	global_load_dwordx4 v[56:59], v79, s[30:31] offset:1024
	global_load_dwordx4 v[60:63], v79, s[30:31] offset:2048
	global_load_dwordx4 v[64:67], v79, s[30:31] offset:3072
	s_add_i32 s14, s35, 3
	s_add_i32 s13, s25, -1
	s_min_i32 s14, s14, s13
	s_lshl_b32 s13, s14, 2
	s_add_i32 s13, s13, s96
	v_mov_b32_e32 v76, s13
	ds_read_b32 v76, v76 offset:16384
	s_cmp_ge_i32 s54, s21
	s_cselect_b32 s14, 1, 0
	s_bfe_u32 s29, s48, 0x40000
	s_cmp_eq_u32 s29, 0
	s_cbranch_scc1 .Lbm2_Ag0_skip
	s_waitcnt vmcnt(12)
	v_mfma_f32_16x16x32_fp8_fp8 v[84:87], v[2:3], v[164:165], 0
	v_mfma_f32_16x16x32_fp8_fp8 v[88:91], v[6:7], v[164:165], 0
	v_mfma_f32_16x16x32_fp8_fp8 v[92:95], v[12:13], v[164:165], 0
	v_mfma_f32_16x16x32_fp8_fp8 v[96:99], v[16:17], v[164:165], 0
	v_mfma_f32_16x16x32_fp8_fp8 v[84:87], v[4:5], v[166:167], v[84:87]
	v_mfma_f32_16x16x32_fp8_fp8 v[88:91], v[8:9], v[166:167], v[88:91]
	v_mfma_f32_16x16x32_fp8_fp8 v[92:95], v[14:15], v[166:167], v[92:95]
	v_mfma_f32_16x16x32_fp8_fp8 v[96:99], v[18:19], v[166:167], v[96:99]
	s_lshr_b32 s83, s48, 4
	s_cmp_lg_u32 s83, 0
	s_cbranch_scc1 .Lbm2_Ag0_kskip
	s_lshl_b32 s83, s32, 12
	s_add_u32 s30, s46, s83
	s_addc_u32 s31, s47, 0
	global_load_dwordx4 v[2:5], v79, s[30:31]
	global_load_dwordx4 v[6:9], v79, s[30:31] offset:1024
	global_load_dwordx4 v[12:15], v79, s[30:31] offset:2048
	global_load_dwordx4 v[16:19], v79, s[30:31] offset:3072
.Lbm2_Ag0_kskip:
	v_and_b32_e32 v199, s29, v244
	s_cmp_eq_u32 s14, 1
	v_cmp_ne_u32_e32 vcc, 0, v199
	s_cbranch_scc1 .Lbm2_Ag0_near
	v_add_f32_e32 v200, v81, v190
	v_cndmask_b32_e32 v200, v77, v200, vcc
	v_pk_fma_f32 v[84:85], v[84:85], s[16:17], v[200:201] op_sel_hi:[1,1,0]
	v_pk_fma_f32 v[86:87], v[86:87], s[16:17], v[200:201] op_sel_hi:[1,1,0]
	v_pk_fma_f32 v[88:89], v[88:89], s[16:17], v[200:201] op_sel_hi:[1,1,0]
	v_pk_fma_f32 v[90:91], v[90:91], s[16:17], v[200:201] op_sel_hi:[1,1,0]
	v_pk_fma_f32 v[92:93], v[92:93], s[16:17], v[200:201] op_sel_hi:[1,1,0]
	v_pk_fma_f32 v[94:95], v[94:95], s[16:17], v[200:201] op_sel_hi:[1,1,0]
	v_pk_fma_f32 v[96:97], v[96:97], s[16:17], v[200:201] op_sel_hi:[1,1,0]
	v_pk_fma_f32 v[98:99], v[98:99], s[16:17], v[200:201] op_sel_hi:[1,1,0]

.Lbm2_Ag0_skip:
	s_bfe_u32 s29, s48, 0x40004
	s_cmp_eq_u32 s29, 0
	s_cbranch_scc1 .Lbm2_Ag1_skip
	s_waitcnt vmcnt(12)
	v_mfma_f32_16x16x32_fp8_fp8 v[84:87], v[2:3], v[168:169], 0
	v_mfma_f32_16x16x32_fp8_fp8 v[88:91], v[6:7], v[168:169], 0
	v_mfma_f32_16x16x32_fp8_fp8 v[92:95], v[12:13], v[168:169], 0
	v_mfma_f32_16x16x32_fp8_fp8 v[96:99], v[16:17], v[168:169], 0
	v_mfma_f32_16x16x32_fp8_fp8 v[84:87], v[4:5], v[170:171], v[84:87]
	v_mfma_f32_16x16x32_fp8_fp8 v[88:91], v[8:9], v[170:171], v[88:91]
	v_mfma_f32_16x16x32_fp8_fp8 v[92:95], v[14:15], v[170:171], v[92:95]
	v_mfma_f32_16x16x32_fp8_fp8 v[96:99], v[18:19], v[170:171], v[96:99]
	s_lshr_b32 s83, s48, 8
	s_cmp_lg_u32 s83, 0
	s_cbranch_scc1 .Lbm2_Ag1_kskip
	s_lshl_b32 s83, s32, 12
	s_add_u32 s30, s46, s83
	s_addc_u32 s31, s47, 0
	global_load_dwordx4 v[2:5], v79, s[30:31]
	global_load_dwordx4 v[6:9], v79, s[30:31] offset:1024
	global_load_dwordx4 v[12:15], v79, s[30:31] offset:2048
	global_load_dwordx4 v[16:19], v79, s[30:31] offset:3072
.Lbm2_Ag1_kskip:
	v_and_b32_e32 v199, s29, v244
	s_cmp_eq_u32 s14, 1
	v_cmp_ne_u32_e32 vcc, 0, v199
	s_cbranch_scc1 .Lbm2_Ag1_near
	v_add_f32_e32 v200, v81, v191
	v_cndmask_b32_e32 v200, v77, v200, vcc
	v_pk_fma_f32 v[84:85], v[84:85], s[16:17], v[200:201] op_sel_hi:[1,1,0]
	v_pk_fma_f32 v[86:87], v[86:87], s[16:17], v[200:201] op_sel_hi:[1,1,0]
	v_pk_fma_f32 v[88:89], v[88:89], s[16:17], v[200:201] op_sel_hi:[1,1,0]
	v_pk_fma_f32 v[90:91], v[90:91], s[16:17], v[200:201] op_sel_hi:[1,1,0]
	v_pk_fma_f32 v[92:93], v[92:93], s[16:17], v[200:201] op_sel_hi:[1,1,0]
	v_pk_fma_f32 v[94:95], v[94:95], s[16:17], v[200:201] op_sel_hi:[1,1,0]
	v_pk_fma_f32 v[96:97], v[96:97], s[16:17], v[200:201] op_sel_hi:[1,1,0]
	v_pk_fma_f32 v[98:99], v[98:99], s[16:17], v[200:201] op_sel_hi:[1,1,0]

.Lbm2_Ag1_skip:
	s_bfe_u32 s29, s48, 0x40008
	s_cmp_eq_u32 s29, 0
	s_cbranch_scc1 .Lbm2_Ag2_skip
	s_waitcnt vmcnt(12)
	v_mfma_f32_16x16x32_fp8_fp8 v[84:87], v[2:3], v[182:183], 0
	v_mfma_f32_16x16x32_fp8_fp8 v[88:91], v[6:7], v[182:183], 0
	v_mfma_f32_16x16x32_fp8_fp8 v[92:95], v[12:13], v[182:183], 0
	v_mfma_f32_16x16x32_fp8_fp8 v[96:99], v[16:17], v[182:183], 0
	v_mfma_f32_16x16x32_fp8_fp8 v[84:87], v[4:5], v[184:185], v[84:87]
	v_mfma_f32_16x16x32_fp8_fp8 v[88:91], v[8:9], v[184:185], v[88:91]
	v_mfma_f32_16x16x32_fp8_fp8 v[92:95], v[14:15], v[184:185], v[92:95]
	v_mfma_f32_16x16x32_fp8_fp8 v[96:99], v[18:19], v[184:185], v[96:99]
	s_lshr_b32 s83, s48, 12
	s_cmp_lg_u32 s83, 0
	s_cbranch_scc1 .Lbm2_Ag2_kskip
	s_lshl_b32 s83, s32, 12
	s_add_u32 s30, s46, s83
	s_addc_u32 s31, s47, 0
	global_load_dwordx4 v[2:5], v79, s[30:31]
	global_load_dwordx4 v[6:9], v79, s[30:31] offset:1024
	global_load_dwordx4 v[12:15], v79, s[30:31] offset:2048
	global_load_dwordx4 v[16:19], v79, s[30:31] offset:3072
.Lbm2_Ag2_kskip:
	v_and_b32_e32 v199, s29, v244
	s_cmp_eq_u32 s14, 1
	v_cmp_ne_u32_e32 vcc, 0, v199
	s_cbranch_scc1 .Lbm2_Ag2_near
	v_add_f32_e32 v200, v81, v192
	v_cndmask_b32_e32 v200, v77, v200, vcc
	v_pk_fma_f32 v[84:85], v[84:85], s[16:17], v[200:201] op_sel_hi:[1,1,0]
	v_pk_fma_f32 v[86:87], v[86:87], s[16:17], v[200:201] op_sel_hi:[1,1,0]
	v_pk_fma_f32 v[88:89], v[88:89], s[16:17], v[200:201] op_sel_hi:[1,1,0]
	v_pk_fma_f32 v[90:91], v[90:91], s[16:17], v[200:201] op_sel_hi:[1,1,0]
	v_pk_fma_f32 v[92:93], v[92:93], s[16:17], v[200:201] op_sel_hi:[1,1,0]
	v_pk_fma_f32 v[94:95], v[94:95], s[16:17], v[200:201] op_sel_hi:[1,1,0]
	v_pk_fma_f32 v[96:97], v[96:97], s[16:17], v[200:201] op_sel_hi:[1,1,0]
	v_pk_fma_f32 v[98:99], v[98:99], s[16:17], v[200:201] op_sel_hi:[1,1,0]

.Lbm2_Ag2_skip:
	s_bfe_u32 s29, s48, 0x4000c
	s_cmp_eq_u32 s29, 0
	s_cbranch_scc1 .Lbm2_Ag3_skip
	s_waitcnt vmcnt(12)
	v_mfma_f32_16x16x32_fp8_fp8 v[84:87], v[2:3], v[186:187], 0
	v_mfma_f32_16x16x32_fp8_fp8 v[88:91], v[6:7], v[186:187], 0
	v_mfma_f32_16x16x32_fp8_fp8 v[92:95], v[12:13], v[186:187], 0
	v_mfma_f32_16x16x32_fp8_fp8 v[96:99], v[16:17], v[186:187], 0
	v_mfma_f32_16x16x32_fp8_fp8 v[84:87], v[4:5], v[188:189], v[84:87]
	v_mfma_f32_16x16x32_fp8_fp8 v[88:91], v[8:9], v[188:189], v[88:91]
	v_mfma_f32_16x16x32_fp8_fp8 v[92:95], v[14:15], v[188:189], v[92:95]
	v_mfma_f32_16x16x32_fp8_fp8 v[96:99], v[18:19], v[188:189], v[96:99]
	s_lshl_b32 s83, s32, 12
	s_add_u32 s30, s46, s83
	s_addc_u32 s31, s47, 0
	global_load_dwordx4 v[2:5], v79, s[30:31]
	global_load_dwordx4 v[6:9], v79, s[30:31] offset:1024
	global_load_dwordx4 v[12:15], v79, s[30:31] offset:2048
	global_load_dwordx4 v[16:19], v79, s[30:31] offset:3072
	v_and_b32_e32 v199, s29, v244
	s_cmp_eq_u32 s14, 1
	v_cmp_ne_u32_e32 vcc, 0, v199
	s_cbranch_scc1 .Lbm2_Ag3_near
	v_add_f32_e32 v200, v81, v193
	v_cndmask_b32_e32 v200, v77, v200, vcc
	v_pk_fma_f32 v[84:85], v[84:85], s[16:17], v[200:201] op_sel_hi:[1,1,0]
	v_pk_fma_f32 v[86:87], v[86:87], s[16:17], v[200:201] op_sel_hi:[1,1,0]
	v_pk_fma_f32 v[88:89], v[88:89], s[16:17], v[200:201] op_sel_hi:[1,1,0]
	v_pk_fma_f32 v[90:91], v[90:91], s[16:17], v[200:201] op_sel_hi:[1,1,0]
	v_pk_fma_f32 v[92:93], v[92:93], s[16:17], v[200:201] op_sel_hi:[1,1,0]
	v_pk_fma_f32 v[94:95], v[94:95], s[16:17], v[200:201] op_sel_hi:[1,1,0]
	v_pk_fma_f32 v[96:97], v[96:97], s[16:17], v[200:201] op_sel_hi:[1,1,0]
	v_pk_fma_f32 v[98:99], v[98:99], s[16:17], v[200:201] op_sel_hi:[1,1,0]

.Lbm2_Ag3_skip:
	v_mov_b32_e32 v78, 0
	s_mov_b32 s54, s15
	s_mov_b32 s48, s27
	s_mov_b32 s15, s32
	s_mov_b32 s27, s55
	s_waitcnt lgkmcnt(0)
	v_readfirstlane_b32 s13, v76
	s_add_i32 s35, s35, 1
	s_and_b32 s32, s13, 0xffff
	s_lshr_b32 s55, s13, 16
	s_cmp_lt_i32 s35, s25
	s_cbranch_scc1 .Lbm2_blkB
	s_branch .Lbm2_done
.Lbm2_blkB:
	s_lshl_b32 s12, s15, 12
	s_add_u32 s30, s62, s12
	s_addc_u32 s31, s63, 0
	global_load_dwordx4 v[36:39], v79, s[30:31]
	global_load_dwordx4 v[40:43], v79, s[30:31] offset:1024
	global_load_dwordx4 v[44:47], v79, s[30:31] offset:2048
	global_load_dwordx4 v[48:51], v79, s[30:31] offset:3072
	s_add_i32 s14, s35, 3
	s_add_i32 s13, s25, -1
	s_min_i32 s14, s14, s13
	s_lshl_b32 s13, s14, 2
	s_add_i32 s13, s13, s96
	v_mov_b32_e32 v76, s13
	ds_read_b32 v76, v76 offset:16384
	s_cmp_ge_i32 s54, s21
	s_cselect_b32 s14, 1, 0
	s_bfe_u32 s29, s48, 0x40000
	s_cmp_eq_u32 s29, 0
	s_cbranch_scc1 .Lbm2_Bg0_skip
	s_waitcnt vmcnt(12)
	v_mfma_f32_16x16x32_fp8_fp8 v[84:87], v[20:21], v[164:165], 0
	v_mfma_f32_16x16x32_fp8_fp8 v[88:91], v[24:25], v[164:165], 0
	v_mfma_f32_16x16x32_fp8_fp8 v[92:95], v[28:29], v[164:165], 0
	v_mfma_f32_16x16x32_fp8_fp8 v[96:99], v[32:33], v[164:165], 0
	v_mfma_f32_16x16x32_fp8_fp8 v[84:87], v[22:23], v[166:167], v[84:87]
	v_mfma_f32_16x16x32_fp8_fp8 v[88:91], v[26:27], v[166:167], v[88:91]
	v_mfma_f32_16x16x32_fp8_fp8 v[92:95], v[30:31], v[166:167], v[92:95]
	v_mfma_f32_16x16x32_fp8_fp8 v[96:99], v[34:35], v[166:167], v[96:99]
	s_lshr_b32 s83, s48, 4
	s_cmp_lg_u32 s83, 0
	s_cbranch_scc1 .Lbm2_Bg0_kskip
	s_lshl_b32 s83, s32, 12
	s_add_u32 s30, s46, s83
	s_addc_u32 s31, s47, 0
	global_load_dwordx4 v[20:23], v79, s[30:31]
	global_load_dwordx4 v[24:27], v79, s[30:31] offset:1024
	global_load_dwordx4 v[28:31], v79, s[30:31] offset:2048
	global_load_dwordx4 v[32:35], v79, s[30:31] offset:3072

.Lbm2_Bg0_skip:
	s_bfe_u32 s29, s48, 0x40004
	s_cmp_eq_u32 s29, 0
	s_cbranch_scc1 .Lbm2_Bg1_skip
	s_waitcnt vmcnt(12)
	v_mfma_f32_16x16x32_fp8_fp8 v[84:87], v[20:21], v[168:169], 0
	v_mfma_f32_16x16x32_fp8_fp8 v[88:91], v[24:25], v[168:169], 0
	v_mfma_f32_16x16x32_fp8_fp8 v[92:95], v[28:29], v[168:169], 0
	v_mfma_f32_16x16x32_fp8_fp8 v[96:99], v[32:33], v[168:169], 0
	v_mfma_f32_16x16x32_fp8_fp8 v[84:87], v[22:23], v[170:171], v[84:87]
	v_mfma_f32_16x16x32_fp8_fp8 v[88:91], v[26:27], v[170:171], v[88:91]
	v_mfma_f32_16x16x32_fp8_fp8 v[92:95], v[30:31], v[170:171], v[92:95]
	v_mfma_f32_16x16x32_fp8_fp8 v[96:99], v[34:35], v[170:171], v[96:99]
	s_lshr_b32 s83, s48, 8
	s_cmp_lg_u32 s83, 0
	s_cbranch_scc1 .Lbm2_Bg1_kskip
	s_lshl_b32 s83, s32, 12
	s_add_u32 s30, s46, s83
	s_addc_u32 s31, s47, 0
	global_load_dwordx4 v[20:23], v79, s[30:31]
	global_load_dwordx4 v[24:27], v79, s[30:31] offset:1024
	global_load_dwordx4 v[28:31], v79, s[30:31] offset:2048
	global_load_dwordx4 v[32:35], v79, s[30:31] offset:3072

.Lbm2_Bg1_skip:
	s_bfe_u32 s29, s48, 0x40008
	s_cmp_eq_u32 s29, 0
	s_cbranch_scc1 .Lbm2_Bg2_skip
	s_waitcnt vmcnt(12)
	v_mfma_f32_16x16x32_fp8_fp8 v[84:87], v[20:21], v[182:183], 0
	v_mfma_f32_16x16x32_fp8_fp8 v[88:91], v[24:25], v[182:183], 0
	v_mfma_f32_16x16x32_fp8_fp8 v[92:95], v[28:29], v[182:183], 0
	v_mfma_f32_16x16x32_fp8_fp8 v[96:99], v[32:33], v[182:183], 0
	v_mfma_f32_16x16x32_fp8_fp8 v[84:87], v[22:23], v[184:185], v[84:87]
	v_mfma_f32_16x16x32_fp8_fp8 v[88:91], v[26:27], v[184:185], v[88:91]
	v_mfma_f32_16x16x32_fp8_fp8 v[92:95], v[30:31], v[184:185], v[92:95]
	v_mfma_f32_16x16x32_fp8_fp8 v[96:99], v[34:35], v[184:185], v[96:99]
	s_lshr_b32 s83, s48, 12
	s_cmp_lg_u32 s83, 0
	s_cbranch_scc1 .Lbm2_Bg2_kskip
	s_lshl_b32 s83, s32, 12
	s_add_u32 s30, s46, s83
	s_addc_u32 s31, s47, 0
	global_load_dwordx4 v[20:23], v79, s[30:31]
	global_load_dwordx4 v[24:27], v79, s[30:31] offset:1024
	global_load_dwordx4 v[28:31], v79, s[30:31] offset:2048
	global_load_dwordx4 v[32:35], v79, s[30:31] offset:3072

.Lbm2_Bg2_skip:
	s_bfe_u32 s29, s48, 0x4000c
	s_cmp_eq_u32 s29, 0
	s_cbranch_scc1 .Lbm2_Bg3_skip
	s_waitcnt vmcnt(12)
	v_mfma_f32_16x16x32_fp8_fp8 v[84:87], v[20:21], v[186:187], 0
	v_mfma_f32_16x16x32_fp8_fp8 v[88:91], v[24:25], v[186:187], 0
	v_mfma_f32_16x16x32_fp8_fp8 v[92:95], v[28:29], v[186:187], 0
	v_mfma_f32_16x16x32_fp8_fp8 v[96:99], v[32:33], v[186:187], 0
	v_mfma_f32_16x16x32_fp8_fp8 v[84:87], v[22:23], v[188:189], v[84:87]
	v_mfma_f32_16x16x32_fp8_fp8 v[88:91], v[26:27], v[188:189], v[88:91]
	v_mfma_f32_16x16x32_fp8_fp8 v[92:95], v[30:31], v[188:189], v[92:95]
	v_mfma_f32_16x16x32_fp8_fp8 v[96:99], v[34:35], v[188:189], v[96:99]
	s_lshl_b32 s83, s32, 12
	s_add_u32 s30, s46, s83
	s_addc_u32 s31, s47, 0
	global_load_dwordx4 v[20:23], v79, s[30:31]
	global_load_dwordx4 v[24:27], v79, s[30:31] offset:1024
	global_load_dwordx4 v[28:31], v79, s[30:31] offset:2048
	global_load_dwordx4 v[32:35], v79, s[30:31] offset:3072
	v_and_b32_e32 v199, s29, v244
	s_cmp_eq_u32 s14, 1
	v_cmp_ne_u32_e32 vcc, 0, v199
	s_cbranch_scc1 .Lbm2_Bg3_near
	v_add_f32_e32 v200, v81, v193
	v_cndmask_b32_e32 v200, v77, v200, vcc
	v_pk_fma_f32 v[84:85], v[84:85], s[16:17], v[200:201] op_sel_hi:[1,1,0]
	v_pk_fma_f32 v[86:87], v[86:87], s[16:17], v[200:201] op_sel_hi:[1,1,0]
	v_pk_fma_f32 v[88:89], v[88:89], s[16:17], v[200:201] op_sel_hi:[1,1,0]
	v_pk_fma_f32 v[90:91], v[90:91], s[16:17], v[200:201] op_sel_hi:[1,1,0]
	v_pk_fma_f32 v[92:93], v[92:93], s[16:17], v[200:201] op_sel_hi:[1,1,0]
	v_pk_fma_f32 v[94:95], v[94:95], s[16:17], v[200:201] op_sel_hi:[1,1,0]
	v_pk_fma_f32 v[96:97], v[96:97], s[16:17], v[200:201] op_sel_hi:[1,1,0]
	v_pk_fma_f32 v[98:99], v[98:99], s[16:17], v[200:201] op_sel_hi:[1,1,0]

.LBB0_2049:
.LBB0_2050:
	v_readfirstlane_b32 s40, v70
	v_readfirstlane_b32 s41, v71
	v_readfirstlane_b32 s62, v72
	v_readfirstlane_b32 s63, v73
	v_and_b32_e32 v248, 15, v181
	v_lshrrev_b32_e32 v249, 4, v181
	v_lshrrev_b32_e32 v248, 2, v248
	v_lshlrev_b32_e32 v249, 2, v249
	v_readlane_b32 s23, v243, 32
	v_mov_b32_e32 v244, 1
	v_lshlrev_b32_e32 v244, v248, v244
	s_mov_b32 s10, 0x3e38aa3b
	s_mov_b32 s11, 0x3e38aa3b
	v_lshlrev_b32_e32 v79, 4, v181
	s_add_i32 s23, s23, s47
	v_add_u32_e32 v247, s23, v248
	v_mad_u64_u32 v[250:251], s[6:7], v247, v212, v[68:69]
	global_load_dwordx4 v[100:103], v[250:251], off
	global_load_dwordx4 v[104:107], v[250:251], off offset:64
	v_add_u32_e32 v249, 4, v247
	v_mad_u64_u32 v[250:251], s[6:7], v249, v212, v[68:69]
	global_load_dwordx4 v[108:111], v[250:251], off
	global_load_dwordx4 v[112:115], v[250:251], off offset:64
	v_add_u32_e32 v249, 8, v247
	v_mad_u64_u32 v[250:251], s[6:7], v249, v212, v[68:69]
	global_load_dwordx4 v[116:119], v[250:251], off
	global_load_dwordx4 v[120:123], v[250:251], off offset:64
	v_add_u32_e32 v249, 12, v247
	v_mad_u64_u32 v[250:251], s[6:7], v249, v212, v[68:69]
	global_load_dwordx4 v[124:127], v[250:251], off
	global_load_dwordx4 v[128:131], v[250:251], off offset:64
	v_and_b32_e32 v248, 15, v181
	v_lshrrev_b32_e32 v249, 4, v181
	v_lshlrev_b32_e32 v198, 6, v248
	v_lshl_add_u32 v198, v249, 2, v198
	v_add_u32_e32 v198, s46, v198
	v_lshl_add_u32 v199, v248, 2, s46
	ds_read_b32 v12, v198 offset:16384
	ds_read_b32 v13, v198 offset:16400
	ds_read_b32 v14, v198 offset:16416
	ds_read_b32 v15, v198 offset:16432
	ds_read_b32 v16, v199 offset:17408
	v_lshl_add_u32 v199, v181, 2, s46
	v_mov_b32_e32 v17, 1
	v_lshlrev_b32_e32 v17, v248, v17
	s_waitcnt lgkmcnt(0)
	v_mul_f32_e32 v81, 0x3fb8aa3b, v81
	ds_write_b32 v199, v11 offset:16384
	ds_write_b32 v199, v11 offset:16640
	ds_write_b32 v199, v11 offset:16896
	ds_write_b32 v199, v11 offset:17152
	v_cmp_lt_i32_e32 vcc, v249, v16
	v_and_b32_e32 v12, 0xff, v12
	v_lshl_add_u32 v12, v12, 2, s46
	v_cndmask_b32_e32 v18, 0, v17, vcc
	ds_or_b32 v12, v18 offset:16384
	v_add_u32_e32 v18, 4, v249
	v_cmp_lt_i32_e32 vcc, v18, v16
	v_and_b32_e32 v13, 0xff, v13
	v_lshl_add_u32 v13, v13, 2, s46
	v_cndmask_b32_e32 v18, 0, v17, vcc
	ds_or_b32 v13, v18 offset:16384
	v_add_u32_e32 v18, 8, v249
	v_cmp_lt_i32_e32 vcc, v18, v16
	v_and_b32_e32 v14, 0xff, v14
	v_lshl_add_u32 v14, v14, 2, s46
	v_cndmask_b32_e32 v18, 0, v17, vcc
	ds_or_b32 v14, v18 offset:16384
	v_add_u32_e32 v18, 12, v249
	v_cmp_lt_i32_e32 vcc, v18, v16
	v_and_b32_e32 v15, 0xff, v15
	v_lshl_add_u32 v15, v15, 2, s46
	v_cndmask_b32_e32 v18, 0, v17, vcc
	ds_or_b32 v15, v18 offset:16384
	s_waitcnt lgkmcnt(0)
	ds_read_b32 v12, v199 offset:16384
	ds_read_b32 v13, v199 offset:16640
	ds_read_b32 v14, v199 offset:16896
	ds_read_b32 v15, v199 offset:17152
	s_mov_b32 s25, 0
	s_waitcnt lgkmcnt(0)
	v_cmp_ne_u32_e64 s[4:5], 0, v12
	v_lshlrev_b32_e32 v16, 16, v12
	v_add_u32_e32 v17, 0, v181
	v_or_b32_e32 v16, v16, v17
	v_mbcnt_lo_u32_b32 v17, s4, 0
	v_mbcnt_hi_u32_b32 v17, s5, v17
	v_add_u32_e32 v17, s25, v17
	v_lshl_add_u32 v17, v17, 2, s46
	v_add_u32_e32 v17, 0x4000, v17
	v_add_u32_e32 v18, 0x4400, v199
	s_bcnt1_i32_b64 s9, s[4:5]
	v_cndmask_b32_e64 v17, v18, v17, s[4:5]
	s_add_i32 s25, s25, s9
	ds_write_b32 v17, v16
	v_cmp_ne_u32_e64 s[4:5], 0, v13
	v_lshlrev_b32_e32 v16, 16, v13
	v_add_u32_e32 v17, 64, v181
	v_or_b32_e32 v16, v16, v17
	v_mbcnt_lo_u32_b32 v17, s4, 0
	v_mbcnt_hi_u32_b32 v17, s5, v17
	v_add_u32_e32 v17, s25, v17
	v_lshl_add_u32 v17, v17, 2, s46
	v_add_u32_e32 v17, 0x4000, v17
	v_add_u32_e32 v18, 0x4400, v199
	s_bcnt1_i32_b64 s9, s[4:5]
	v_cndmask_b32_e64 v17, v18, v17, s[4:5]
	s_add_i32 s25, s25, s9
	ds_write_b32 v17, v16
	v_cmp_ne_u32_e64 s[4:5], 0, v14
	v_lshlrev_b32_e32 v16, 16, v14
	v_add_u32_e32 v17, 128, v181
	v_or_b32_e32 v16, v16, v17
	v_mbcnt_lo_u32_b32 v17, s4, 0
	v_mbcnt_hi_u32_b32 v17, s5, v17
	v_add_u32_e32 v17, s25, v17
	v_lshl_add_u32 v17, v17, 2, s46
	v_add_u32_e32 v17, 0x4000, v17
	v_add_u32_e32 v18, 0x4400, v199
	s_bcnt1_i32_b64 s9, s[4:5]
	v_cndmask_b32_e64 v17, v18, v17, s[4:5]
	s_add_i32 s25, s25, s9
	ds_write_b32 v17, v16
	v_cmp_ne_u32_e64 s[4:5], 0, v15
	v_lshlrev_b32_e32 v16, 16, v15
	v_add_u32_e32 v17, 192, v181
	v_or_b32_e32 v16, v16, v17
	v_mbcnt_lo_u32_b32 v17, s4, 0
	v_mbcnt_hi_u32_b32 v17, s5, v17
	v_add_u32_e32 v17, s25, v17
	v_lshl_add_u32 v17, v17, 2, s46
	v_add_u32_e32 v17, 0x4000, v17
	v_add_u32_e32 v18, 0x4400, v199
	s_bcnt1_i32_b64 s9, s[4:5]
	v_cndmask_b32_e64 v17, v18, v17, s[4:5]
	s_add_i32 s25, s25, s9
	ds_write_b32 v17, v16
	s_waitcnt vmcnt(0)
	v_lshlrev_b32_e32 v245, 16, v100
	v_and_b32_e32 v246, 0xffff0000, v100
	v_mul_f32_e32 v245, 0x41000000, v245
	v_mul_f32_e32 v246, 0x41000000, v246
	v_lshlrev_b32_e32 v248, 16, v101
	v_and_b32_e32 v249, 0xffff0000, v101
	v_cvt_pk_fp8_f32 v164, v245, v246
	v_mul_f32_e32 v248, 0x41000000, v248
	v_mul_f32_e32 v249, 0x41000000, v249
	s_nop 0
	v_cvt_pk_fp8_f32 v164, v248, v249 op_sel:[0,0,1]
	v_lshlrev_b32_e32 v245, 16, v102
	v_and_b32_e32 v246, 0xffff0000, v102
	v_mul_f32_e32 v245, 0x41000000, v245
	v_mul_f32_e32 v246, 0x41000000, v246
	v_lshlrev_b32_e32 v248, 16, v103
	v_and_b32_e32 v249, 0xffff0000, v103
	v_cvt_pk_fp8_f32 v165, v245, v246
	v_mul_f32_e32 v248, 0x41000000, v248
	v_mul_f32_e32 v249, 0x41000000, v249
	s_nop 0
	v_cvt_pk_fp8_f32 v165, v248, v249 op_sel:[0,0,1]
	v_lshlrev_b32_e32 v245, 16, v104
	v_and_b32_e32 v246, 0xffff0000, v104
	v_mul_f32_e32 v245, 0x41000000, v245
	v_mul_f32_e32 v246, 0x41000000, v246
	v_lshlrev_b32_e32 v248, 16, v105
	v_and_b32_e32 v249, 0xffff0000, v105
	v_cvt_pk_fp8_f32 v166, v245, v246
	v_mul_f32_e32 v248, 0x41000000, v248
	v_mul_f32_e32 v249, 0x41000000, v249
	s_nop 0
	v_cvt_pk_fp8_f32 v166, v248, v249 op_sel:[0,0,1]
	v_lshlrev_b32_e32 v245, 16, v106
	v_and_b32_e32 v246, 0xffff0000, v106
	v_mul_f32_e32 v245, 0x41000000, v245
	v_mul_f32_e32 v246, 0x41000000, v246
	v_lshlrev_b32_e32 v248, 16, v107
	v_and_b32_e32 v249, 0xffff0000, v107
	v_cvt_pk_fp8_f32 v167, v245, v246
	v_mul_f32_e32 v248, 0x41000000, v248
	v_mul_f32_e32 v249, 0x41000000, v249
	s_nop 0
	v_cvt_pk_fp8_f32 v167, v248, v249 op_sel:[0,0,1]
	v_lshlrev_b32_e32 v245, 16, v108
	v_and_b32_e32 v246, 0xffff0000, v108
	v_mul_f32_e32 v245, 0x41000000, v245
	v_mul_f32_e32 v246, 0x41000000, v246
	v_lshlrev_b32_e32 v248, 16, v109
	v_and_b32_e32 v249, 0xffff0000, v109
	v_cvt_pk_fp8_f32 v168, v245, v246
	v_mul_f32_e32 v248, 0x41000000, v248
	v_mul_f32_e32 v249, 0x41000000, v249
	s_nop 0
	v_cvt_pk_fp8_f32 v168, v248, v249 op_sel:[0,0,1]
	v_lshlrev_b32_e32 v245, 16, v110
	v_and_b32_e32 v246, 0xffff0000, v110
	v_mul_f32_e32 v245, 0x41000000, v245
	v_mul_f32_e32 v246, 0x41000000, v246
	v_lshlrev_b32_e32 v248, 16, v111
	v_and_b32_e32 v249, 0xffff0000, v111
	v_cvt_pk_fp8_f32 v169, v245, v246
	v_mul_f32_e32 v248, 0x41000000, v248
	v_mul_f32_e32 v249, 0x41000000, v249
	s_nop 0
	v_cvt_pk_fp8_f32 v169, v248, v249 op_sel:[0,0,1]
	v_lshlrev_b32_e32 v245, 16, v112
	v_and_b32_e32 v246, 0xffff0000, v112
	v_mul_f32_e32 v245, 0x41000000, v245
	v_mul_f32_e32 v246, 0x41000000, v246
	v_lshlrev_b32_e32 v248, 16, v113
	v_and_b32_e32 v249, 0xffff0000, v113
	v_cvt_pk_fp8_f32 v170, v245, v246
	v_mul_f32_e32 v248, 0x41000000, v248
	v_mul_f32_e32 v249, 0x41000000, v249
	s_nop 0
	v_cvt_pk_fp8_f32 v170, v248, v249 op_sel:[0,0,1]
	v_lshlrev_b32_e32 v245, 16, v114
	v_and_b32_e32 v246, 0xffff0000, v114
	v_mul_f32_e32 v245, 0x41000000, v245
	v_mul_f32_e32 v246, 0x41000000, v246
	v_lshlrev_b32_e32 v248, 16, v115
	v_and_b32_e32 v249, 0xffff0000, v115
	v_cvt_pk_fp8_f32 v171, v245, v246
	v_mul_f32_e32 v248, 0x41000000, v248
	v_mul_f32_e32 v249, 0x41000000, v249
	s_nop 0
	v_cvt_pk_fp8_f32 v171, v248, v249 op_sel:[0,0,1]
	v_lshlrev_b32_e32 v245, 16, v116
	v_and_b32_e32 v246, 0xffff0000, v116
	v_mul_f32_e32 v245, 0x41000000, v245
	v_mul_f32_e32 v246, 0x41000000, v246
	v_lshlrev_b32_e32 v248, 16, v117
	v_and_b32_e32 v249, 0xffff0000, v117
	v_cvt_pk_fp8_f32 v182, v245, v246
	v_mul_f32_e32 v248, 0x41000000, v248
	v_mul_f32_e32 v249, 0x41000000, v249
	s_nop 0
	v_cvt_pk_fp8_f32 v182, v248, v249 op_sel:[0,0,1]
	v_lshlrev_b32_e32 v245, 16, v118
	v_and_b32_e32 v246, 0xffff0000, v118
	v_mul_f32_e32 v245, 0x41000000, v245
	v_mul_f32_e32 v246, 0x41000000, v246
	v_lshlrev_b32_e32 v248, 16, v119
	v_and_b32_e32 v249, 0xffff0000, v119
	v_cvt_pk_fp8_f32 v183, v245, v246
	v_mul_f32_e32 v248, 0x41000000, v248
	v_mul_f32_e32 v249, 0x41000000, v249
	s_nop 0
	v_cvt_pk_fp8_f32 v183, v248, v249 op_sel:[0,0,1]
	v_lshlrev_b32_e32 v245, 16, v120
	v_and_b32_e32 v246, 0xffff0000, v120
	v_mul_f32_e32 v245, 0x41000000, v245
	v_mul_f32_e32 v246, 0x41000000, v246
	v_lshlrev_b32_e32 v248, 16, v121
	v_and_b32_e32 v249, 0xffff0000, v121
	v_cvt_pk_fp8_f32 v184, v245, v246
	v_mul_f32_e32 v248, 0x41000000, v248
	v_mul_f32_e32 v249, 0x41000000, v249
	s_nop 0
	v_cvt_pk_fp8_f32 v184, v248, v249 op_sel:[0,0,1]
	v_lshlrev_b32_e32 v245, 16, v122
	v_and_b32_e32 v246, 0xffff0000, v122
	v_mul_f32_e32 v245, 0x41000000, v245
	v_mul_f32_e32 v246, 0x41000000, v246
	v_lshlrev_b32_e32 v248, 16, v123
	v_and_b32_e32 v249, 0xffff0000, v123
	v_cvt_pk_fp8_f32 v185, v245, v246
	v_mul_f32_e32 v248, 0x41000000, v248
	v_mul_f32_e32 v249, 0x41000000, v249
	s_nop 0
	v_cvt_pk_fp8_f32 v185, v248, v249 op_sel:[0,0,1]
	v_lshlrev_b32_e32 v245, 16, v124
	v_and_b32_e32 v246, 0xffff0000, v124
	v_mul_f32_e32 v245, 0x41000000, v245
	v_mul_f32_e32 v246, 0x41000000, v246
	v_lshlrev_b32_e32 v248, 16, v125
	v_and_b32_e32 v249, 0xffff0000, v125
	v_cvt_pk_fp8_f32 v186, v245, v246
	v_mul_f32_e32 v248, 0x41000000, v248
	v_mul_f32_e32 v249, 0x41000000, v249
	s_nop 0
	v_cvt_pk_fp8_f32 v186, v248, v249 op_sel:[0,0,1]
	v_lshlrev_b32_e32 v245, 16, v126
	v_and_b32_e32 v246, 0xffff0000, v126
	v_mul_f32_e32 v245, 0x41000000, v245
	v_mul_f32_e32 v246, 0x41000000, v246
	v_lshlrev_b32_e32 v248, 16, v127
	v_and_b32_e32 v249, 0xffff0000, v127
	v_cvt_pk_fp8_f32 v187, v245, v246
	v_mul_f32_e32 v248, 0x41000000, v248
	v_mul_f32_e32 v249, 0x41000000, v249
	s_nop 0
	v_cvt_pk_fp8_f32 v187, v248, v249 op_sel:[0,0,1]
	v_lshlrev_b32_e32 v245, 16, v128
	v_and_b32_e32 v246, 0xffff0000, v128
	v_mul_f32_e32 v245, 0x41000000, v245
	v_mul_f32_e32 v246, 0x41000000, v246
	v_lshlrev_b32_e32 v248, 16, v129
	v_and_b32_e32 v249, 0xffff0000, v129
	v_cvt_pk_fp8_f32 v188, v245, v246
	v_mul_f32_e32 v248, 0x41000000, v248
	v_mul_f32_e32 v249, 0x41000000, v249
	s_nop 0
	v_cvt_pk_fp8_f32 v188, v248, v249 op_sel:[0,0,1]
	v_lshlrev_b32_e32 v245, 16, v130
	v_and_b32_e32 v246, 0xffff0000, v130
	v_mul_f32_e32 v245, 0x41000000, v245
	v_mul_f32_e32 v246, 0x41000000, v246
	v_lshlrev_b32_e32 v248, 16, v131
	v_and_b32_e32 v249, 0xffff0000, v131
	v_cvt_pk_fp8_f32 v189, v245, v246
	v_mul_f32_e32 v248, 0x41000000, v248
	v_mul_f32_e32 v249, 0x41000000, v249
	s_nop 0
	v_cvt_pk_fp8_f32 v189, v248, v249 op_sel:[0,0,1]
	v_mov_b64_e32 v[100:101], 0
	v_mov_b64_e32 v[102:103], 0
	v_mov_b64_e32 v[104:105], 0
	v_mov_b64_e32 v[106:107], 0
	v_mov_b64_e32 v[108:109], 0
	v_mov_b64_e32 v[110:111], 0
	v_mov_b64_e32 v[112:113], 0
	v_mov_b64_e32 v[114:115], 0
	v_mov_b32_e32 v190, 0
	v_mov_b32_e32 v194, 0
	v_mov_b64_e32 v[116:117], 0
	v_mov_b64_e32 v[118:119], 0
	v_mov_b64_e32 v[120:121], 0
	v_mov_b64_e32 v[122:123], 0
	v_mov_b64_e32 v[124:125], 0
	v_mov_b64_e32 v[126:127], 0
	v_mov_b64_e32 v[128:129], 0
	v_mov_b64_e32 v[130:131], 0
	v_mov_b32_e32 v191, 0
	v_mov_b32_e32 v195, 0
	v_mov_b64_e32 v[132:133], 0
	v_mov_b64_e32 v[134:135], 0
	v_mov_b64_e32 v[136:137], 0
	v_mov_b64_e32 v[138:139], 0
	v_mov_b64_e32 v[140:141], 0
	v_mov_b64_e32 v[142:143], 0
	v_mov_b64_e32 v[144:145], 0
	v_mov_b64_e32 v[146:147], 0
	v_mov_b32_e32 v192, 0
	v_mov_b32_e32 v196, 0
	v_mov_b64_e32 v[148:149], 0
	v_mov_b64_e32 v[150:151], 0
	v_mov_b64_e32 v[152:153], 0
	v_mov_b64_e32 v[154:155], 0
	v_mov_b64_e32 v[156:157], 0
	v_mov_b64_e32 v[158:159], 0
	v_mov_b64_e32 v[160:161], 0
	v_mov_b64_e32 v[162:163], 0
	v_mov_b32_e32 v193, 0
	v_mov_b32_e32 v197, 0
	v_mov_b32_e32 v77, 0xff800000
	v_mov_b32_e32 v78, 0xff800000
	s_waitcnt lgkmcnt(0)
	s_mov_b32 s35, 0
	s_lshl_b32 s9, s35, 2
	s_add_i32 s9, s9, s46
	v_mov_b32_e32 v76, s9
	ds_read_b32 v76, v76 offset:16384
	s_add_i32 s50, s25, -1
	s_min_i32 s50, s50, 1
	s_waitcnt lgkmcnt(0)
	v_readfirstlane_b32 s9, v76
	s_and_b32 s38, s9, 0xffff
	s_lshr_b32 s48, s9, 16
	s_lshl_b32 s9, s50, 2
	s_add_i32 s9, s9, s46
	v_mov_b32_e32 v76, s9
	ds_read_b32 v76, v76 offset:16384
	s_lshl_b32 s29, s38, 12
	s_add_u32 s30, s40, s29
	s_addc_u32 s31, s41, 0
	global_load_dwordx4 v[2:5], v79, s[30:31]
	global_load_dwordx4 v[6:9], v79, s[30:31] offset:1024
	global_load_dwordx4 v[12:15], v79, s[30:31] offset:2048
	global_load_dwordx4 v[16:19], v79, s[30:31] offset:3072
	s_lshl_b32 s29, s38, 12
	s_add_u32 s30, s62, s29
	s_addc_u32 s31, s63, 0
	global_load_dwordx4 v[36:39], v79, s[30:31]
	global_load_dwordx4 v[40:43], v79, s[30:31] offset:1024
	global_load_dwordx4 v[44:47], v79, s[30:31] offset:2048
	global_load_dwordx4 v[48:51], v79, s[30:31] offset:3072
	s_waitcnt lgkmcnt(0)
	v_readfirstlane_b32 s9, v76
	s_and_b32 s27, s9, 0xffff
	s_lshr_b32 s8, s9, 16
	s_add_i32 s83, s25, -1
	s_min_i32 s83, s83, 2
	s_lshl_b32 s83, s83, 2
	s_add_i32 s83, s83, s46
	v_mov_b32_e32 v76, s83
	ds_read_b32 v76, v76 offset:16384
	s_lshl_b32 s83, s27, 12
	s_add_u32 s30, s40, s83
	s_addc_u32 s31, s41, 0
	global_load_dwordx4 v[20:23], v79, s[30:31]
	global_load_dwordx4 v[24:27], v79, s[30:31] offset:1024
	global_load_dwordx4 v[28:31], v79, s[30:31] offset:2048
	global_load_dwordx4 v[32:35], v79, s[30:31] offset:3072
	s_waitcnt lgkmcnt(0)
	v_readfirstlane_b32 s9, v76
	s_and_b32 s32, s9, 0xffff
	s_lshr_b32 s55, s9, 16
.Lbm3_blkA:
	s_lshl_b32 s29, s27, 12
	s_add_u32 s30, s62, s29
	s_addc_u32 s31, s63, 0
	global_load_dwordx4 v[52:55], v79, s[30:31]
	global_load_dwordx4 v[56:59], v79, s[30:31] offset:1024
	global_load_dwordx4 v[60:63], v79, s[30:31] offset:2048
	global_load_dwordx4 v[64:67], v79, s[30:31] offset:3072
	s_add_i32 s50, s35, 3
	s_add_i32 s9, s25, -1
	s_min_i32 s50, s50, s9
	s_lshl_b32 s9, s50, 2
	s_add_i32 s9, s9, s46
	v_mov_b32_e32 v76, s9
	ds_read_b32 v76, v76 offset:16384
	s_cmp_ge_i32 s38, s21
	s_cselect_b32 s50, 1, 0
	s_bfe_u32 s29, s48, 0x40000
	s_cmp_eq_u32 s29, 0
	s_cbranch_scc1 .Lbm3_Ag0_skip
	s_waitcnt vmcnt(12)
	v_mfma_f32_16x16x32_fp8_fp8 v[84:87], v[2:3], v[164:165], 0
	v_mfma_f32_16x16x32_fp8_fp8 v[88:91], v[6:7], v[164:165], 0
	v_mfma_f32_16x16x32_fp8_fp8 v[92:95], v[12:13], v[164:165], 0
	v_mfma_f32_16x16x32_fp8_fp8 v[96:99], v[16:17], v[164:165], 0
	v_mfma_f32_16x16x32_fp8_fp8 v[84:87], v[4:5], v[166:167], v[84:87]
	v_mfma_f32_16x16x32_fp8_fp8 v[88:91], v[8:9], v[166:167], v[88:91]
	v_mfma_f32_16x16x32_fp8_fp8 v[92:95], v[14:15], v[166:167], v[92:95]
	v_mfma_f32_16x16x32_fp8_fp8 v[96:99], v[18:19], v[166:167], v[96:99]
	s_lshr_b32 s83, s48, 4
	s_cmp_lg_u32 s83, 0
	s_cbranch_scc1 .Lbm3_Ag0_kskip
	s_lshl_b32 s83, s32, 12
	s_add_u32 s30, s40, s83
	s_addc_u32 s31, s41, 0
	global_load_dwordx4 v[2:5], v79, s[30:31]
	global_load_dwordx4 v[6:9], v79, s[30:31] offset:1024
	global_load_dwordx4 v[12:15], v79, s[30:31] offset:2048
	global_load_dwordx4 v[16:19], v79, s[30:31] offset:3072
.Lbm3_Ag0_kskip:
	v_and_b32_e32 v199, s29, v244
	s_cmp_eq_u32 s50, 1
	v_cmp_ne_u32_e32 vcc, 0, v199
	s_cbranch_scc1 .Lbm3_Ag0_near
	v_add_f32_e32 v200, v81, v190
	v_cndmask_b32_e32 v200, v77, v200, vcc
	v_pk_fma_f32 v[84:85], v[84:85], s[10:11], v[200:201] op_sel_hi:[1,1,0]
	v_pk_fma_f32 v[86:87], v[86:87], s[10:11], v[200:201] op_sel_hi:[1,1,0]
	v_pk_fma_f32 v[88:89], v[88:89], s[10:11], v[200:201] op_sel_hi:[1,1,0]
	v_pk_fma_f32 v[90:91], v[90:91], s[10:11], v[200:201] op_sel_hi:[1,1,0]
	v_pk_fma_f32 v[92:93], v[92:93], s[10:11], v[200:201] op_sel_hi:[1,1,0]
	v_pk_fma_f32 v[94:95], v[94:95], s[10:11], v[200:201] op_sel_hi:[1,1,0]
	v_pk_fma_f32 v[96:97], v[96:97], s[10:11], v[200:201] op_sel_hi:[1,1,0]
	v_pk_fma_f32 v[98:99], v[98:99], s[10:11], v[200:201] op_sel_hi:[1,1,0]

.Lbm3_Ag0_skip:
	s_bfe_u32 s29, s48, 0x40004
	s_cmp_eq_u32 s29, 0
	s_cbranch_scc1 .Lbm3_Ag1_skip
	s_waitcnt vmcnt(12)
	v_mfma_f32_16x16x32_fp8_fp8 v[84:87], v[2:3], v[168:169], 0
	v_mfma_f32_16x16x32_fp8_fp8 v[88:91], v[6:7], v[168:169], 0
	v_mfma_f32_16x16x32_fp8_fp8 v[92:95], v[12:13], v[168:169], 0
	v_mfma_f32_16x16x32_fp8_fp8 v[96:99], v[16:17], v[168:169], 0
	v_mfma_f32_16x16x32_fp8_fp8 v[84:87], v[4:5], v[170:171], v[84:87]
	v_mfma_f32_16x16x32_fp8_fp8 v[88:91], v[8:9], v[170:171], v[88:91]
	v_mfma_f32_16x16x32_fp8_fp8 v[92:95], v[14:15], v[170:171], v[92:95]
	v_mfma_f32_16x16x32_fp8_fp8 v[96:99], v[18:19], v[170:171], v[96:99]
	s_lshr_b32 s83, s48, 8
	s_cmp_lg_u32 s83, 0
	s_cbranch_scc1 .Lbm3_Ag1_kskip
	s_lshl_b32 s83, s32, 12
	s_add_u32 s30, s40, s83
	s_addc_u32 s31, s41, 0
	global_load_dwordx4 v[2:5], v79, s[30:31]
	global_load_dwordx4 v[6:9], v79, s[30:31] offset:1024
	global_load_dwordx4 v[12:15], v79, s[30:31] offset:2048
	global_load_dwordx4 v[16:19], v79, s[30:31] offset:3072
.Lbm3_Ag1_kskip:
	v_and_b32_e32 v199, s29, v244
	s_cmp_eq_u32 s50, 1
	v_cmp_ne_u32_e32 vcc, 0, v199
	s_cbranch_scc1 .Lbm3_Ag1_near
	v_add_f32_e32 v200, v81, v191
	v_cndmask_b32_e32 v200, v77, v200, vcc
	v_pk_fma_f32 v[84:85], v[84:85], s[10:11], v[200:201] op_sel_hi:[1,1,0]
	v_pk_fma_f32 v[86:87], v[86:87], s[10:11], v[200:201] op_sel_hi:[1,1,0]
	v_pk_fma_f32 v[88:89], v[88:89], s[10:11], v[200:201] op_sel_hi:[1,1,0]
	v_pk_fma_f32 v[90:91], v[90:91], s[10:11], v[200:201] op_sel_hi:[1,1,0]
	v_pk_fma_f32 v[92:93], v[92:93], s[10:11], v[200:201] op_sel_hi:[1,1,0]
	v_pk_fma_f32 v[94:95], v[94:95], s[10:11], v[200:201] op_sel_hi:[1,1,0]
	v_pk_fma_f32 v[96:97], v[96:97], s[10:11], v[200:201] op_sel_hi:[1,1,0]
	v_pk_fma_f32 v[98:99], v[98:99], s[10:11], v[200:201] op_sel_hi:[1,1,0]

.Lbm3_Ag1_skip:
	s_bfe_u32 s29, s48, 0x40008
	s_cmp_eq_u32 s29, 0
	s_cbranch_scc1 .Lbm3_Ag2_skip
	s_waitcnt vmcnt(12)
	v_mfma_f32_16x16x32_fp8_fp8 v[84:87], v[2:3], v[182:183], 0
	v_mfma_f32_16x16x32_fp8_fp8 v[88:91], v[6:7], v[182:183], 0
	v_mfma_f32_16x16x32_fp8_fp8 v[92:95], v[12:13], v[182:183], 0
	v_mfma_f32_16x16x32_fp8_fp8 v[96:99], v[16:17], v[182:183], 0
	v_mfma_f32_16x16x32_fp8_fp8 v[84:87], v[4:5], v[184:185], v[84:87]
	v_mfma_f32_16x16x32_fp8_fp8 v[88:91], v[8:9], v[184:185], v[88:91]
	v_mfma_f32_16x16x32_fp8_fp8 v[92:95], v[14:15], v[184:185], v[92:95]
	v_mfma_f32_16x16x32_fp8_fp8 v[96:99], v[18:19], v[184:185], v[96:99]
	s_lshr_b32 s83, s48, 12
	s_cmp_lg_u32 s83, 0
	s_cbranch_scc1 .Lbm3_Ag2_kskip
	s_lshl_b32 s83, s32, 12
	s_add_u32 s30, s40, s83
	s_addc_u32 s31, s41, 0
	global_load_dwordx4 v[2:5], v79, s[30:31]
	global_load_dwordx4 v[6:9], v79, s[30:31] offset:1024
	global_load_dwordx4 v[12:15], v79, s[30:31] offset:2048
	global_load_dwordx4 v[16:19], v79, s[30:31] offset:3072
.Lbm3_Ag2_kskip:
	v_and_b32_e32 v199, s29, v244
	s_cmp_eq_u32 s50, 1
	v_cmp_ne_u32_e32 vcc, 0, v199
	s_cbranch_scc1 .Lbm3_Ag2_near
	v_add_f32_e32 v200, v81, v192
	v_cndmask_b32_e32 v200, v77, v200, vcc
	v_pk_fma_f32 v[84:85], v[84:85], s[10:11], v[200:201] op_sel_hi:[1,1,0]
	v_pk_fma_f32 v[86:87], v[86:87], s[10:11], v[200:201] op_sel_hi:[1,1,0]
	v_pk_fma_f32 v[88:89], v[88:89], s[10:11], v[200:201] op_sel_hi:[1,1,0]
	v_pk_fma_f32 v[90:91], v[90:91], s[10:11], v[200:201] op_sel_hi:[1,1,0]
	v_pk_fma_f32 v[92:93], v[92:93], s[10:11], v[200:201] op_sel_hi:[1,1,0]
	v_pk_fma_f32 v[94:95], v[94:95], s[10:11], v[200:201] op_sel_hi:[1,1,0]
	v_pk_fma_f32 v[96:97], v[96:97], s[10:11], v[200:201] op_sel_hi:[1,1,0]
	v_pk_fma_f32 v[98:99], v[98:99], s[10:11], v[200:201] op_sel_hi:[1,1,0]

.Lbm3_Ag2_skip:
	s_bfe_u32 s29, s48, 0x4000c
	s_cmp_eq_u32 s29, 0
	s_cbranch_scc1 .Lbm3_Ag3_skip
	s_waitcnt vmcnt(12)
	v_mfma_f32_16x16x32_fp8_fp8 v[84:87], v[2:3], v[186:187], 0
	v_mfma_f32_16x16x32_fp8_fp8 v[88:91], v[6:7], v[186:187], 0
	v_mfma_f32_16x16x32_fp8_fp8 v[92:95], v[12:13], v[186:187], 0
	v_mfma_f32_16x16x32_fp8_fp8 v[96:99], v[16:17], v[186:187], 0
	v_mfma_f32_16x16x32_fp8_fp8 v[84:87], v[4:5], v[188:189], v[84:87]
	v_mfma_f32_16x16x32_fp8_fp8 v[88:91], v[8:9], v[188:189], v[88:91]
	v_mfma_f32_16x16x32_fp8_fp8 v[92:95], v[14:15], v[188:189], v[92:95]
	v_mfma_f32_16x16x32_fp8_fp8 v[96:99], v[18:19], v[188:189], v[96:99]
	s_lshl_b32 s83, s32, 12
	s_add_u32 s30, s40, s83
	s_addc_u32 s31, s41, 0
	global_load_dwordx4 v[2:5], v79, s[30:31]
	global_load_dwordx4 v[6:9], v79, s[30:31] offset:1024
	global_load_dwordx4 v[12:15], v79, s[30:31] offset:2048
	global_load_dwordx4 v[16:19], v79, s[30:31] offset:3072
	v_and_b32_e32 v199, s29, v244
	s_cmp_eq_u32 s50, 1
	v_cmp_ne_u32_e32 vcc, 0, v199
	s_cbranch_scc1 .Lbm3_Ag3_near
	v_add_f32_e32 v200, v81, v193
	v_cndmask_b32_e32 v200, v77, v200, vcc
	v_pk_fma_f32 v[84:85], v[84:85], s[10:11], v[200:201] op_sel_hi:[1,1,0]
	v_pk_fma_f32 v[86:87], v[86:87], s[10:11], v[200:201] op_sel_hi:[1,1,0]
	v_pk_fma_f32 v[88:89], v[88:89], s[10:11], v[200:201] op_sel_hi:[1,1,0]
	v_pk_fma_f32 v[90:91], v[90:91], s[10:11], v[200:201] op_sel_hi:[1,1,0]
	v_pk_fma_f32 v[92:93], v[92:93], s[10:11], v[200:201] op_sel_hi:[1,1,0]
	v_pk_fma_f32 v[94:95], v[94:95], s[10:11], v[200:201] op_sel_hi:[1,1,0]
	v_pk_fma_f32 v[96:97], v[96:97], s[10:11], v[200:201] op_sel_hi:[1,1,0]
	v_pk_fma_f32 v[98:99], v[98:99], s[10:11], v[200:201] op_sel_hi:[1,1,0]

.Lbm3_Ag3_skip:
	v_mov_b32_e32 v78, 0
	s_mov_b32 s38, s27
	s_mov_b32 s48, s8
	s_mov_b32 s27, s32
	s_mov_b32 s8, s55
	s_waitcnt lgkmcnt(0)
	v_readfirstlane_b32 s9, v76
	s_add_i32 s35, s35, 1
	s_and_b32 s32, s9, 0xffff
	s_lshr_b32 s55, s9, 16
	s_cmp_lt_i32 s35, s25
	s_cbranch_scc1 .Lbm3_blkB
	s_branch .Lbm3_done
.Lbm3_blkB:
	s_lshl_b32 s29, s27, 12
	s_add_u32 s30, s62, s29
	s_addc_u32 s31, s63, 0
	global_load_dwordx4 v[36:39], v79, s[30:31]
	global_load_dwordx4 v[40:43], v79, s[30:31] offset:1024
	global_load_dwordx4 v[44:47], v79, s[30:31] offset:2048
	global_load_dwordx4 v[48:51], v79, s[30:31] offset:3072
	s_add_i32 s50, s35, 3
	s_add_i32 s9, s25, -1
	s_min_i32 s50, s50, s9
	s_lshl_b32 s9, s50, 2
	s_add_i32 s9, s9, s46
	v_mov_b32_e32 v76, s9
	ds_read_b32 v76, v76 offset:16384
	s_cmp_ge_i32 s38, s21
	s_cselect_b32 s50, 1, 0
	s_bfe_u32 s29, s48, 0x40000
	s_cmp_eq_u32 s29, 0
	s_cbranch_scc1 .Lbm3_Bg0_skip
	s_waitcnt vmcnt(12)
	v_mfma_f32_16x16x32_fp8_fp8 v[84:87], v[20:21], v[164:165], 0
	v_mfma_f32_16x16x32_fp8_fp8 v[88:91], v[24:25], v[164:165], 0
	v_mfma_f32_16x16x32_fp8_fp8 v[92:95], v[28:29], v[164:165], 0
	v_mfma_f32_16x16x32_fp8_fp8 v[96:99], v[32:33], v[164:165], 0
	v_mfma_f32_16x16x32_fp8_fp8 v[84:87], v[22:23], v[166:167], v[84:87]
	v_mfma_f32_16x16x32_fp8_fp8 v[88:91], v[26:27], v[166:167], v[88:91]
	v_mfma_f32_16x16x32_fp8_fp8 v[92:95], v[30:31], v[166:167], v[92:95]
	v_mfma_f32_16x16x32_fp8_fp8 v[96:99], v[34:35], v[166:167], v[96:99]
	s_lshr_b32 s83, s48, 4
	s_cmp_lg_u32 s83, 0
	s_cbranch_scc1 .Lbm3_Bg0_kskip
	s_lshl_b32 s83, s32, 12
	s_add_u32 s30, s40, s83
	s_addc_u32 s31, s41, 0
	global_load_dwordx4 v[20:23], v79, s[30:31]
	global_load_dwordx4 v[24:27], v79, s[30:31] offset:1024
	global_load_dwordx4 v[28:31], v79, s[30:31] offset:2048
	global_load_dwordx4 v[32:35], v79, s[30:31] offset:3072

.Lbm3_Bg0_skip:
	s_bfe_u32 s29, s48, 0x40004
	s_cmp_eq_u32 s29, 0
	s_cbranch_scc1 .Lbm3_Bg1_skip
	s_waitcnt vmcnt(12)
	v_mfma_f32_16x16x32_fp8_fp8 v[84:87], v[20:21], v[168:169], 0
	v_mfma_f32_16x16x32_fp8_fp8 v[88:91], v[24:25], v[168:169], 0
	v_mfma_f32_16x16x32_fp8_fp8 v[92:95], v[28:29], v[168:169], 0
	v_mfma_f32_16x16x32_fp8_fp8 v[96:99], v[32:33], v[168:169], 0
	v_mfma_f32_16x16x32_fp8_fp8 v[84:87], v[22:23], v[170:171], v[84:87]
	v_mfma_f32_16x16x32_fp8_fp8 v[88:91], v[26:27], v[170:171], v[88:91]
	v_mfma_f32_16x16x32_fp8_fp8 v[92:95], v[30:31], v[170:171], v[92:95]
	v_mfma_f32_16x16x32_fp8_fp8 v[96:99], v[34:35], v[170:171], v[96:99]
	s_lshr_b32 s83, s48, 8
	s_cmp_lg_u32 s83, 0
	s_cbranch_scc1 .Lbm3_Bg1_kskip
	s_lshl_b32 s83, s32, 12
	s_add_u32 s30, s40, s83
	s_addc_u32 s31, s41, 0
	global_load_dwordx4 v[20:23], v79, s[30:31]
	global_load_dwordx4 v[24:27], v79, s[30:31] offset:1024
	global_load_dwordx4 v[28:31], v79, s[30:31] offset:2048
	global_load_dwordx4 v[32:35], v79, s[30:31] offset:3072

.Lbm3_Bg1_skip:
	s_bfe_u32 s29, s48, 0x40008
	s_cmp_eq_u32 s29, 0
	s_cbranch_scc1 .Lbm3_Bg2_skip
	s_waitcnt vmcnt(12)
	v_mfma_f32_16x16x32_fp8_fp8 v[84:87], v[20:21], v[182:183], 0
	v_mfma_f32_16x16x32_fp8_fp8 v[88:91], v[24:25], v[182:183], 0
	v_mfma_f32_16x16x32_fp8_fp8 v[92:95], v[28:29], v[182:183], 0
	v_mfma_f32_16x16x32_fp8_fp8 v[96:99], v[32:33], v[182:183], 0
	v_mfma_f32_16x16x32_fp8_fp8 v[84:87], v[22:23], v[184:185], v[84:87]
	v_mfma_f32_16x16x32_fp8_fp8 v[88:91], v[26:27], v[184:185], v[88:91]
	v_mfma_f32_16x16x32_fp8_fp8 v[92:95], v[30:31], v[184:185], v[92:95]
	v_mfma_f32_16x16x32_fp8_fp8 v[96:99], v[34:35], v[184:185], v[96:99]
	s_lshr_b32 s83, s48, 12
	s_cmp_lg_u32 s83, 0
	s_cbranch_scc1 .Lbm3_Bg2_kskip
	s_lshl_b32 s83, s32, 12
	s_add_u32 s30, s40, s83
	s_addc_u32 s31, s41, 0
	global_load_dwordx4 v[20:23], v79, s[30:31]
	global_load_dwordx4 v[24:27], v79, s[30:31] offset:1024
	global_load_dwordx4 v[28:31], v79, s[30:31] offset:2048
	global_load_dwordx4 v[32:35], v79, s[30:31] offset:3072

.Lbm3_Bg2_skip:
	s_bfe_u32 s29, s48, 0x4000c
	s_cmp_eq_u32 s29, 0
	s_cbranch_scc1 .Lbm3_Bg3_skip
	s_waitcnt vmcnt(12)
	v_mfma_f32_16x16x32_fp8_fp8 v[84:87], v[20:21], v[186:187], 0
	v_mfma_f32_16x16x32_fp8_fp8 v[88:91], v[24:25], v[186:187], 0
	v_mfma_f32_16x16x32_fp8_fp8 v[92:95], v[28:29], v[186:187], 0
	v_mfma_f32_16x16x32_fp8_fp8 v[96:99], v[32:33], v[186:187], 0
	v_mfma_f32_16x16x32_fp8_fp8 v[84:87], v[22:23], v[188:189], v[84:87]
	v_mfma_f32_16x16x32_fp8_fp8 v[88:91], v[26:27], v[188:189], v[88:91]
	v_mfma_f32_16x16x32_fp8_fp8 v[92:95], v[30:31], v[188:189], v[92:95]
	v_mfma_f32_16x16x32_fp8_fp8 v[96:99], v[34:35], v[188:189], v[96:99]
	s_lshl_b32 s83, s32, 12
	s_add_u32 s30, s40, s83
	s_addc_u32 s31, s41, 0
	global_load_dwordx4 v[20:23], v79, s[30:31]
	global_load_dwordx4 v[24:27], v79, s[30:31] offset:1024
	global_load_dwordx4 v[28:31], v79, s[30:31] offset:2048
	global_load_dwordx4 v[32:35], v79, s[30:31] offset:3072
	v_and_b32_e32 v199, s29, v244
	s_cmp_eq_u32 s50, 1
	v_cmp_ne_u32_e32 vcc, 0, v199
	s_cbranch_scc1 .Lbm3_Bg3_near
	v_add_f32_e32 v200, v81, v193
	v_cndmask_b32_e32 v200, v77, v200, vcc
	v_pk_fma_f32 v[84:85], v[84:85], s[10:11], v[200:201] op_sel_hi:[1,1,0]
	v_pk_fma_f32 v[86:87], v[86:87], s[10:11], v[200:201] op_sel_hi:[1,1,0]
	v_pk_fma_f32 v[88:89], v[88:89], s[10:11], v[200:201] op_sel_hi:[1,1,0]
	v_pk_fma_f32 v[90:91], v[90:91], s[10:11], v[200:201] op_sel_hi:[1,1,0]
	v_pk_fma_f32 v[92:93], v[92:93], s[10:11], v[200:201] op_sel_hi:[1,1,0]
	v_pk_fma_f32 v[94:95], v[94:95], s[10:11], v[200:201] op_sel_hi:[1,1,0]
	v_pk_fma_f32 v[96:97], v[96:97], s[10:11], v[200:201] op_sel_hi:[1,1,0]
	v_pk_fma_f32 v[98:99], v[98:99], s[10:11], v[200:201] op_sel_hi:[1,1,0]
